# prologue: adaLN workgroups keep 7 of 10 item rounds, other waves take the rest (static rebalance)
# baseline (speedup 1.0000x reference)
.LBB0_18:
	s_lshl_b32 s92, s2, 3
	s_lshl_b32 s48, s46, 3
	s_add_i32 s44, s45, s92
	s_cmpk_gt_i32 s44, 0x4d00
	s_waitcnt lgkmcnt(0)
	s_barrier
	s_cbranch_scc1 .LBB0_63
	v_lshlrev_b32_e32 v4, 3, v1
	s_lshl_b32 s4, s45, 14
	v_lshrrev_b32_e32 v44, 3, v1
	v_and_b32_e32 v12, 56, v4
	s_add_i32 s45, s4, 0
	v_lshrrev_b32_e32 v43, 5, v1
	v_mul_u32_u24_e32 v4, 0x84, v12
	v_lshlrev_b32_e32 v5, 2, v44
	v_mov_b32_e32 v11, 0
	v_add3_u32 v45, s45, v4, v5
	v_mul_u32_u24_e32 v4, 0x84, v43
	v_lshlrev_b32_e32 v5, 2, v22
	s_add_u32 s49, s14, 0x100000
	v_lshlrev_b32_e32 v2, 2, v1
	v_lshrrev_b32_e32 v13, 1, v1
	v_or_b32_e32 v4, s4, v4
	v_and_b32_e32 v14, 0x7c, v5
	v_mov_b32_e32 v15, v11
	s_addc_u32 s50, s15, 0
	v_and_b32_e32 v2, 4, v2
	v_or_b32_e32 v19, 32, v13
	v_or_b32_e32 v23, 64, v13
	v_or_b32_e32 v42, 0x60, v13
	v_add3_u32 v50, v4, v14, 0
	v_lshl_add_u64 v[4:5], s[22:23], 0, v[14:15]
	s_mov_b64 s[4:5], 0x200000
	v_lshlrev_b32_e32 v10, 6, v1
	v_lshl_add_u32 v3, v2, 2, s45
	v_lshlrev_b32_e32 v6, 5, v13
	v_lshlrev_b32_e32 v7, 5, v19
	v_lshlrev_b32_e32 v8, 5, v23
	v_lshlrev_b32_e32 v9, 5, v42
	s_add_u32 s51, s30, 16
	v_lshl_add_u64 v[16:17], v[4:5], 0, s[4:5]
	v_bfe_u32 v18, v22, 5, 1
	v_lshl_add_u64 v[4:5], s[14:15], 0, v[10:11]
	s_mov_b64 s[4:5], 0x60000
	s_mov_b32 s29, 0
	v_or_b32_e32 v46, 8, v44
	v_or_b32_e32 v47, 16, v44
	v_or_b32_e32 v48, 24, v44
	v_cvt_f32_ubyte0_e32 v49, v1
	s_addc_u32 s52, s31, 0
	v_or_b32_e32 v51, 0xffffb90e, v43
	v_or_b32_e32 v52, 0xffffb90c, v43
	v_or_b32_e32 v53, 0xffffb90a, v43
	v_or_b32_e32 v54, 0xffffb908, v43
	v_or_b32_e32 v55, 0xffffb906, v43
	v_or_b32_e32 v56, 0xffffb904, v43
	v_or_b32_e32 v57, 0xffffb902, v43
	v_or_b32_e32 v58, 0xffffb900, v43
	v_or_b32_e32 v59, 14, v43
	v_or_b32_e32 v60, 12, v43
	v_or_b32_e32 v61, 10, v43
	v_or_b32_e32 v62, 8, v43
	v_or_b32_e32 v63, 6, v43
	v_or_b32_e32 v64, 4, v43
	v_or_b32_e32 v65, 2, v43
	v_lshl_or_b32 v20, v18, 12, v14
	v_mov_b32_e32 v21, v11
	v_lshl_add_u64 v[24:25], v[4:5], 0, s[4:5]
	v_lshlrev_b32_e32 v26, 2, v2
	v_add_u32_e32 v66, v3, v6
	v_add_u32_e32 v67, v3, v7
	v_add_u32_e32 v68, v3, v8
	v_add_u32_e32 v69, v3, v9
	s_movk_i32 s53, 0x7fff
	s_mov_b64 s[30:31], 0x1300400
	s_mov_b32 s54, 0xffff0000
	s_movk_i32 s55, 0x1400
	s_mov_b64 s[34:35], 0x1080000
	s_movk_i32 s56, 0xe480
	s_brev_b32 s57, 64
	s_movk_i32 s58, 0x5800
	s_mov_b32 s59, 0x3f2aaaab
	v_mov_b32_e32 v70, 0x3e91f4c4
	s_mov_b32 s60, 0x3f317218
	s_movk_i32 s61, 0x204
	s_mov_b32 s62, 0x7f800000
	s_mov_b32 s63, 0x42b17218
	s_mov_b32 s64, 0x3fb8aa3b
	s_mov_b32 s65, 0xc2ce8ed0
	s_brev_b32 s66, 18
	s_mov_b32 s67, 0xfe5163ab
	s_mov_b32 s68, 0x3c439041
	s_mov_b32 s69, 0xdb629599
	s_mov_b32 s70, 0xf534ddc0
	s_mov_b32 s71, 0xfc2757d1
	s_mov_b32 s72, 0x4e441529
	s_mov_b32 s73, 0xa2f9836e
	s_mov_b32 s74, 0x3fc90fda
	s_mov_b32 s75, 0x3f22f983
	s_mov_b32 s76, 0xbfc90fda
	v_mov_b32_e32 v71, 0x3c0881c4
	v_mov_b32_e32 v72, 0xbab64f3b
	s_brev_b32 s77, 1
	s_movk_i32 s78, 0x1f8
	v_mov_b32_e32 v73, 0xb00000
	v_mov_b32_e32 v74, 0x461c4000
	v_mov_b32_e32 v75, 0x37000000
	v_mov_b32_e32 v76, 0x7f800000
	v_not_b32_e32 v77, 63
	v_not_b32_e32 v78, 31
	v_mov_b32_e32 v79, 0x7fc00000
	v_lshl_add_u64 v[28:29], s[8:9], 0, v[14:15]
	s_mov_b32 s84, 0
	s_sub_i32 s85, s44, 0x240
	s_branch .LBB0_21
.LBB0_20:
	s_cmpk_eq_i32 s48, 0x800
	s_cbranch_scc0 .Lit_orig
	s_cmp_lt_u32 s2, 0x48
	s_cbranch_scc0 .Lit_other
	s_add_i32 s44, s44, s48
	s_cmpk_lt_i32 s44, 0x3800
	s_cbranch_scc1 .LBB0_21
	s_branch .LBB0_63
.Lit_other:
	s_cmp_lg_u32 s84, 0
	s_cbranch_scc1 .Lit_extra
	s_add_i32 s44, s44, s48
	s_cmpk_gt_i32 s44, 0x4d00
	s_cbranch_scc0 .LBB0_21
	s_mov_b32 s84, 1
.Lit_extra:
	s_cmpk_ge_i32 s85, 0x6c0
	s_cbranch_scc1 .LBB0_63
	s_mul_i32 s86, s85, 0xe39
	s_lshr_b32 s86, s86, 21
	s_mul_i32 s87, s86, 0x240
	s_sub_i32 s87, s85, s87
	s_add_i32 s86, s86, 7
	s_lshl_b32 s86, s86, 11
	s_add_i32 s44, s86, s87
	s_addk_i32 s85, 0x5c0
	s_branch .LBB0_21
